# four P8 edits + prologue/serial-chain de-serialisation of sp_prefetch: 6-step per-lane binary search over the list prefix column replaced by a 2-round 8-ary search (14 independent LDS reads)
# baseline (speedup 1.0000x reference)
; #define LAS __attribute__((address_space(3)))
; __device__ __forceinline__ void dma_kv_imgs(LAS unsigned char* Kimg, LAS unsigned char* Vimg, const f16_t* ksrc, const f16_t* vsrc, int wave, int lane, int pitch = NB) {
;     const int rl = lane >> 3, pos = lane & 7;
;     const int kc = pos ^ rl, vc = 2 * ((pos >> 1) ^ ((lane >> 4) & 3)) + (pos & 1);
;     const unsigned kd = (unsigned)__builtin_amdgcn_readfirstlane((int)(unsigned)(uintptr_t)Kimg), vd = (unsigned)__builtin_amdgcn_readfirstlane((int)(unsigned)(uintptr_t)Vimg);
; #pragma unroll
;     for (int i = 0; i < 4; ++i) { const int pc = wave + 8 * i, row = 8 * pc + rl;
;         glds16_asm(ksrc + (size_t)row * pitch + 8 * kc, (unsigned)__builtin_amdgcn_readfirstlane((int)(kd + pc * 1024)));
;         glds16_asm(vsrc + (size_t)row * pitch + 8 * vc, (unsigned)__builtin_amdgcn_readfirstlane((int)(vd + pc * 1024))); }
; __device__ __forceinline__ void sp_prefetch(int it, int bh, LAS const int* IP, LAS const int* NJ, LAS const unsigned short* cum, LAS const unsigned short* offs, const unsigned short* LIST, ...
;     int l2 = 0, h2 = 64; while (h2 - l2 > 1) { const int mid = (l2 + h2) >> 1; if (IP[mid] <= it) l2 = mid; else h2 = mid; }
;     const int j = l2, part = it - IP[l2], b = bh / MOBA_H, h = bh % MOBA_H;
;     int n = NJ[j] - part * SP_PART; if (n > SP_PART) n = SP_PART; o.n = n; o.j = j;
;     const f16_t* kb = P + (size_t)(b * SEQ + j * MOBA_BLK) * NB + MIXW + h * HD;
;     dma_kv_imgs(img, img + 32768, kb, kb + MIXW, wave, lane);
;     const int ei = (lane < 32) ? 32 * wave + lane : 256 + 32 * wave + (lane - 32);
;     if (ei < n) { const int e = part * SP_PART + ei; const LAS unsigned short* cj = cum + j; int lq = 0, hq = 64;
;         while (hq - lq > 1) { const int mid = (lq + hq) >> 1; if ((int)cj[mid * NBLK] <= e) lq = mid; else hq = mid; }
;         o.lq = lq;
;         o.raw = LIST[((size_t)bh * NBLK + lq) * LIST_CAP + offs[lq * OFFS_LD + j] + (e - (int)cj[lq * NBLK])]; }
.LBB0_1140:
	s_add_i32 s42, s40, s70
	s_ashr_i32 s42, s42, 1
	s_lshl_b32 s43, s42, 2
	s_add_i32 s43, s43, 0
	s_add_i32 s43, s43, 0x24300
	v_mov_b32_e32 v46, s43
	ds_read_b32 v46, v46
	s_waitcnt lgkmcnt(0)
	v_readfirstlane_b32 s43, v46
	s_cmp_gt_i32 s43, s30
	s_cselect_b32 s40, s42, s40
	s_cselect_b32 s70, s70, s42
	s_sub_i32 s42, s40, s70
	s_cmp_gt_i32 s42, 1
	s_cbranch_scc1 .LBB0_1140
	s_lshl_b32 s40, s70, 2
	s_add_i32 s40, s40, 0
	s_add_i32 s42, s40, 0x24300
	s_add_i32 s40, s40, 0x24200
	v_mov_b32_e32 v46, s42
	v_mov_b32_e32 v68, s40
	ds_read_b32 v46, v46
	ds_read_b32 v68, v68
	v_lshlrev_b64 v[124:125], 1, v[52:53]
	s_waitcnt lgkmcnt(1)
	v_readfirstlane_b32 s40, v46
	s_sub_i32 s40, s30, s40
	s_waitcnt lgkmcnt(0)
	v_readfirstlane_b32 s42, v68
	s_lshl_b32 s71, s40, 9
	s_sub_i32 s40, s42, s71
	s_lshl_b32 s42, s70, 8
	s_add_i32 s42, s42, s25
	s_min_i32 s40, s40, 0x200
	s_mul_hi_i32 s43, s42, 0x1400
	s_mulk_i32 s42, 0x1400
	s_add_u32 s42, s26, s42
	s_addc_u32 s43, s27, s43
	v_lshlrev_b32_e32 v46, 1, v50
	v_lshl_add_u64 v[68:69], s[42:43], 0, v[46:47]
	v_lshlrev_b32_e32 v46, 1, v54
	v_lshl_add_u64 v[122:123], s[42:43], 0, v[46:47]
	v_lshl_add_u64 v[68:69], v[68:69], 0, s[66:67]
	v_lshl_add_u64 v[122:123], v[122:123], 0, s[72:73]
	v_lshl_add_u64 v[126:127], v[68:69], 0, v[124:125]
	s_add_i32 s42, s87, s37
	s_mov_b32 s43, m0
	s_mov_b32 m0, s42
	s_nop 0
	global_load_lds_dwordx4 v[126:127], off
	s_mov_b32 m0, s43
	v_lshl_add_u64 v[124:125], v[122:123], 0, v[124:125]
	s_add_i32 s42, s87, s38
	s_mov_b32 s43, m0
	s_mov_b32 m0, s42
	s_nop 0
	global_load_lds_dwordx4 v[124:125], off
	s_mov_b32 m0, s43
	v_lshlrev_b64 v[124:125], 1, v[56:57]
	v_lshl_add_u64 v[126:127], v[68:69], 0, v[124:125]
	s_add_i32 s42, s81, s37
	s_mov_b32 s43, m0
	s_mov_b32 m0, s42
	s_nop 0
	global_load_lds_dwordx4 v[126:127], off
	s_mov_b32 m0, s43
	v_lshl_add_u64 v[124:125], v[122:123], 0, v[124:125]
	s_add_i32 s42, s81, s38
	s_mov_b32 s43, m0
	s_mov_b32 m0, s42
	s_nop 0
	global_load_lds_dwordx4 v[124:125], off
	s_mov_b32 m0, s43
	v_lshlrev_b64 v[124:125], 1, v[58:59]
	v_lshl_add_u64 v[126:127], v[68:69], 0, v[124:125]
	s_add_i32 s42, s12, s37
	s_mov_b32 s43, m0
	s_mov_b32 m0, s42
	s_nop 0
	global_load_lds_dwordx4 v[126:127], off
	s_mov_b32 m0, s43
	v_lshl_add_u64 v[124:125], v[122:123], 0, v[124:125]
	s_add_i32 s42, s12, s38
	s_mov_b32 s43, m0
	s_mov_b32 m0, s42
	s_nop 0
	global_load_lds_dwordx4 v[124:125], off
	s_mov_b32 m0, s43
	v_lshlrev_b64 v[124:125], 1, v[60:61]
	v_lshl_add_u64 v[68:69], v[68:69], 0, v[124:125]
	s_add_i32 s42, s13, s37
	s_mov_b32 s43, m0
	s_mov_b32 m0, s42
	s_nop 0
	global_load_lds_dwordx4 v[68:69], off
	s_mov_b32 m0, s43
	v_lshl_add_u64 v[68:69], v[122:123], 0, v[124:125]
	s_add_i32 s42, s13, s38
	s_mov_b32 s43, m0
	s_mov_b32 m0, s42
	s_nop 0
	global_load_lds_dwordx4 v[68:69], off
	s_mov_b32 m0, s43
	v_cmp_gt_i32_e32 vcc, s40, v90
	v_mov_b32_e32 v69, v19
	v_mov_b32_e32 v68, v18
	s_and_saveexec_b64 s[54:55], vcc
	s_cbranch_execz .LBB0_1145
	s_lshl_b32 s42, s70, 1
	s_add_i32 s42, s42, 0
	v_add_u32_e32 v46, s71, v90
	s_add_i32 s43, s42, 0x22200
	v_mov_b32_e32 v69, s43
	ds_read_u16 v242, v69 offset:1024
	ds_read_u16 v243, v69 offset:2048
	ds_read_u16 v244, v69 offset:3072
	ds_read_u16 v245, v69 offset:4096
	ds_read_u16 v246, v69 offset:5120
	ds_read_u16 v247, v69 offset:6144
	ds_read_u16 v248, v69 offset:7168
	s_waitcnt lgkmcnt(0)
	v_sub_u32_e32 v242, v46, v242
	v_sub_u32_e32 v243, v46, v243
	v_sub_u32_e32 v244, v46, v244
	v_sub_u32_e32 v245, v46, v245
	v_sub_u32_e32 v246, v46, v246
	v_sub_u32_e32 v247, v46, v247
	v_sub_u32_e32 v248, v46, v248
	v_ashrrev_i32_e32 v242, 31, v242
	v_ashrrev_i32_e32 v243, 31, v243
	v_ashrrev_i32_e32 v244, 31, v244
	v_ashrrev_i32_e32 v245, 31, v245
	v_ashrrev_i32_e32 v246, 31, v246
	v_ashrrev_i32_e32 v247, 31, v247
	v_ashrrev_i32_e32 v248, 31, v248
	v_add3_u32 v68, v242, v243, v244
	v_add3_u32 v68, v68, v245, v246
	v_add3_u32 v68, v68, v247, v248
	v_add_u32_e32 v68, 7, v68
	v_lshlrev_b32_e32 v68, 3, v68
	v_lshl_add_u32 v69, v68, 7, s43
	ds_read_u16 v242, v69 offset:128
	ds_read_u16 v243, v69 offset:256
	ds_read_u16 v244, v69 offset:384
	ds_read_u16 v245, v69 offset:512
	ds_read_u16 v246, v69 offset:640
	ds_read_u16 v247, v69 offset:768
	ds_read_u16 v248, v69 offset:896
	s_waitcnt lgkmcnt(0)
	v_sub_u32_e32 v242, v46, v242
	v_sub_u32_e32 v243, v46, v243
	v_sub_u32_e32 v244, v46, v244
	v_sub_u32_e32 v245, v46, v245
	v_sub_u32_e32 v246, v46, v246
	v_sub_u32_e32 v247, v46, v247
	v_sub_u32_e32 v248, v46, v248
	v_ashrrev_i32_e32 v242, 31, v242
	v_ashrrev_i32_e32 v243, 31, v243
	v_ashrrev_i32_e32 v244, 31, v244
	v_ashrrev_i32_e32 v245, 31, v245
	v_ashrrev_i32_e32 v246, 31, v246
	v_ashrrev_i32_e32 v247, 31, v247
	v_ashrrev_i32_e32 v248, 31, v248
	v_add3_u32 v242, v242, v243, v244
	v_add3_u32 v242, v242, v245, v246
	v_add3_u32 v242, v242, v247, v248
	v_add3_u32 v68, v68, v242, 7
	v_mul_lo_u32 v69, v68, s20
	v_add_u32_e32 v69, s42, v69
	v_lshl_add_u32 v115, v68, 7, s43
	v_add_u32_e32 v69, 0x20000, v69
	ds_read_u16 v115, v115
	ds_read_u16 v116, v69
	v_ashrrev_i32_e32 v69, 31, v68
	v_lshl_add_u64 v[122:123], s[96:97], 0, v[68:69]
	v_mov_b64_e32 v[126:127], s[82:83]
	v_mad_u64_u32 v[126:127], s[42:43], v122, s21, v[126:127]
	s_waitcnt lgkmcnt(1)
	v_sub_u32_e32 v124, v46, v115
	v_mad_i32_i24 v127, v123, s21, v127
	s_waitcnt lgkmcnt(0)
	v_lshlrev_b32_e32 v46, 1, v116
	v_ashrrev_i32_e32 v125, 31, v124
	v_lshl_add_u64 v[122:123], v[126:127], 0, v[46:47]
	v_lshl_add_u64 v[122:123], v[124:125], 1, v[122:123]
	global_load_ushort v69, v[122:123], off

; #define LAS __attribute__((address_space(3)))
; __device__ __forceinline__ void dma_kv_imgs(LAS unsigned char* Kimg, LAS unsigned char* Vimg, const f16_t* ksrc, const f16_t* vsrc, int wave, int lane, int pitch = NB) {
;     const int rl = lane >> 3, pos = lane & 7;
;     const int kc = pos ^ rl, vc = 2 * ((pos >> 1) ^ ((lane >> 4) & 3)) + (pos & 1);
;     const unsigned kd = (unsigned)__builtin_amdgcn_readfirstlane((int)(unsigned)(uintptr_t)Kimg), vd = (unsigned)__builtin_amdgcn_readfirstlane((int)(unsigned)(uintptr_t)Vimg);
; #pragma unroll
;     for (int i = 0; i < 4; ++i) { const int pc = wave + 8 * i, row = 8 * pc + rl;
;         glds16_asm(ksrc + (size_t)row * pitch + 8 * kc, (unsigned)__builtin_amdgcn_readfirstlane((int)(kd + pc * 1024)));
;         glds16_asm(vsrc + (size_t)row * pitch + 8 * vc, (unsigned)__builtin_amdgcn_readfirstlane((int)(vd + pc * 1024))); }
; __device__ __forceinline__ void sp_prefetch(int it, int bh, LAS const int* IP, LAS const int* NJ, LAS const unsigned short* cum, LAS const unsigned short* offs, const unsigned short* LIST, ...
;     int l2 = 0, h2 = 64; while (h2 - l2 > 1) { const int mid = (l2 + h2) >> 1; if (IP[mid] <= it) l2 = mid; else h2 = mid; }
;     const int j = l2, part = it - IP[l2], b = bh / MOBA_H, h = bh % MOBA_H;
;     int n = NJ[j] - part * SP_PART; if (n > SP_PART) n = SP_PART; o.n = n; o.j = j;
;     const f16_t* kb = P + (size_t)(b * SEQ + j * MOBA_BLK) * NB + MIXW + h * HD;
;     dma_kv_imgs(img, img + 32768, kb, kb + MIXW, wave, lane);
;     const int ei = (lane < 32) ? 32 * wave + lane : 256 + 32 * wave + (lane - 32);
;     if (ei < n) { const int e = part * SP_PART + ei; const LAS unsigned short* cj = cum + j; int lq = 0, hq = 64;
;         while (hq - lq > 1) { const int mid = (lq + hq) >> 1; if ((int)cj[mid * NBLK] <= e) lq = mid; else hq = mid; }
;         o.lq = lq;
;         o.raw = LIST[((size_t)bh * NBLK + lq) * LIST_CAP + offs[lq * OFFS_LD + j] + (e - (int)cj[lq * NBLK])]; }
.LBB0_1161:
	s_add_i32 s7, s6, s8
	s_ashr_i32 s7, s7, 1
	s_lshl_b32 s9, s7, 2
	s_add_i32 s9, s9, 0
	s_add_i32 s9, s9, 0x24300
	v_mov_b32_e32 v20, s9
	ds_read_b32 v20, v20
	s_waitcnt lgkmcnt(0)
	v_readfirstlane_b32 s9, v20
	s_cmp_gt_i32 s9, s30
	s_cselect_b32 s6, s7, s6
	s_cselect_b32 s8, s8, s7
	s_sub_i32 s7, s6, s8
	s_cmp_gt_i32 s7, 1
	s_cbranch_scc1 .LBB0_1161
	s_lshl_b32 s7, s8, 2
	s_add_i32 s7, s7, 0
	s_add_i32 s9, s7, 0x24300
	v_mov_b32_e32 v20, s9
	ds_read_b32 v20, v20
	s_add_i32 s7, s7, 0x24200
	v_mov_b32_e32 v21, s7
	ds_read_b32 v21, v21
	s_xor_b32 s6, s34, 0x10000
	s_add_i32 s31, s6, 0
	s_waitcnt lgkmcnt(1)
	v_readfirstlane_b32 s6, v20
	s_sub_i32 s6, s30, s6
	s_lshl_b32 s9, s6, 9
	s_waitcnt lgkmcnt(0)
	v_readfirstlane_b32 s6, v21
	s_sub_i32 s6, s6, s9
	s_min_i32 s41, s6, 0x200
	s_lshl_b32 s6, s8, 8
	s_add_i32 s6, s6, s25
	s_mul_hi_i32 s7, s6, 0x1400
	s_mulk_i32 s6, 0x1400
	s_add_u32 s6, s26, s6
	s_addc_u32 s7, s27, s7
	v_lshlrev_b32_e32 v46, 1, v50
	v_lshl_add_u64 v[20:21], s[6:7], 0, v[46:47]
	v_lshlrev_b32_e32 v46, 1, v54
	v_lshl_add_u64 v[22:23], s[6:7], 0, v[46:47]
	v_lshl_add_u64 v[20:21], v[20:21], 0, s[66:67]
	v_lshl_add_u64 v[22:23], v[22:23], 0, s[72:73]
	v_lshlrev_b64 v[24:25], 1, v[52:53]
	s_add_i32 s30, s31, 0x8000
	v_lshl_add_u64 v[26:27], v[20:21], 0, v[24:25]
	s_add_i32 s6, s87, s31
	s_mov_b32 s7, m0
	s_mov_b32 m0, s6
	s_nop 0
	global_load_lds_dwordx4 v[26:27], off
	s_mov_b32 m0, s7
	v_lshl_add_u64 v[24:25], v[22:23], 0, v[24:25]
	s_add_i32 s6, s87, s30
	s_mov_b32 s7, m0
	s_mov_b32 m0, s6
	s_nop 0
	global_load_lds_dwordx4 v[24:25], off
	s_mov_b32 m0, s7
	v_lshlrev_b64 v[24:25], 1, v[56:57]
	v_lshl_add_u64 v[26:27], v[20:21], 0, v[24:25]
	s_add_i32 s6, s81, s31
	s_mov_b32 s7, m0
	s_mov_b32 m0, s6
	s_nop 0
	global_load_lds_dwordx4 v[26:27], off
	s_mov_b32 m0, s7
	v_lshl_add_u64 v[24:25], v[22:23], 0, v[24:25]
	s_add_i32 s6, s81, s30
	s_mov_b32 s7, m0
	s_mov_b32 m0, s6
	s_nop 0
	global_load_lds_dwordx4 v[24:25], off
	s_mov_b32 m0, s7
	v_lshlrev_b64 v[24:25], 1, v[58:59]
	v_lshl_add_u64 v[26:27], v[20:21], 0, v[24:25]
	s_add_i32 s6, s12, s31
	s_mov_b32 s7, m0
	s_mov_b32 m0, s6
	s_nop 0
	global_load_lds_dwordx4 v[26:27], off
	s_mov_b32 m0, s7
	v_lshl_add_u64 v[24:25], v[22:23], 0, v[24:25]
	s_add_i32 s6, s12, s30
	s_mov_b32 s7, m0
	s_mov_b32 m0, s6
	s_nop 0
	global_load_lds_dwordx4 v[24:25], off
	s_mov_b32 m0, s7
	v_lshlrev_b64 v[24:25], 1, v[60:61]
	v_lshl_add_u64 v[20:21], v[20:21], 0, v[24:25]
	s_add_i32 s6, s13, s31
	s_mov_b32 s7, m0
	s_mov_b32 m0, s6
	s_nop 0
	global_load_lds_dwordx4 v[20:21], off
	s_mov_b32 m0, s7
	v_lshl_add_u64 v[20:21], v[22:23], 0, v[24:25]
	s_add_i32 s6, s13, s30
	s_mov_b32 s7, m0
	s_mov_b32 m0, s6
	s_nop 0
	global_load_lds_dwordx4 v[20:21], off
	s_mov_b32 m0, s7
	v_cmp_gt_i32_e32 vcc, s41, v90
	s_and_saveexec_b64 s[6:7], vcc
	s_cbranch_execz .LBB0_1166
	s_lshl_b32 s8, s8, 1
	s_add_i32 s30, s8, 0
	v_add_u32_e32 v20, s9, v90
	s_add_i32 s31, s30, 0x22200
	v_mov_b32_e32 v19, s31
	ds_read_u16 v242, v19 offset:1024
	ds_read_u16 v243, v19 offset:2048
	ds_read_u16 v244, v19 offset:3072
	ds_read_u16 v245, v19 offset:4096
	ds_read_u16 v246, v19 offset:5120
	ds_read_u16 v247, v19 offset:6144
	ds_read_u16 v248, v19 offset:7168
	s_waitcnt lgkmcnt(0)
	v_sub_u32_e32 v242, v20, v242
	v_sub_u32_e32 v243, v20, v243
	v_sub_u32_e32 v244, v20, v244
	v_sub_u32_e32 v245, v20, v245
	v_sub_u32_e32 v246, v20, v246
	v_sub_u32_e32 v247, v20, v247
	v_sub_u32_e32 v248, v20, v248
	v_ashrrev_i32_e32 v242, 31, v242
	v_ashrrev_i32_e32 v243, 31, v243
	v_ashrrev_i32_e32 v244, 31, v244
	v_ashrrev_i32_e32 v245, 31, v245
	v_ashrrev_i32_e32 v246, 31, v246
	v_ashrrev_i32_e32 v247, 31, v247
	v_ashrrev_i32_e32 v248, 31, v248
	v_add3_u32 v18, v242, v243, v244
	v_add3_u32 v18, v18, v245, v246
	v_add3_u32 v18, v18, v247, v248
	v_add_u32_e32 v18, 7, v18
	v_lshlrev_b32_e32 v18, 3, v18
	v_lshl_add_u32 v19, v18, 7, s31
	ds_read_u16 v242, v19 offset:128
	ds_read_u16 v243, v19 offset:256
	ds_read_u16 v244, v19 offset:384
	ds_read_u16 v245, v19 offset:512
	ds_read_u16 v246, v19 offset:640
	ds_read_u16 v247, v19 offset:768
	ds_read_u16 v248, v19 offset:896
	s_waitcnt lgkmcnt(0)
	v_sub_u32_e32 v242, v20, v242
	v_sub_u32_e32 v243, v20, v243
	v_sub_u32_e32 v244, v20, v244
	v_sub_u32_e32 v245, v20, v245
	v_sub_u32_e32 v246, v20, v246
	v_sub_u32_e32 v247, v20, v247
	v_sub_u32_e32 v248, v20, v248
	v_ashrrev_i32_e32 v242, 31, v242
	v_ashrrev_i32_e32 v243, 31, v243
	v_ashrrev_i32_e32 v244, 31, v244
	v_ashrrev_i32_e32 v245, 31, v245
	v_ashrrev_i32_e32 v246, 31, v246
	v_ashrrev_i32_e32 v247, 31, v247
	v_ashrrev_i32_e32 v248, 31, v248
	v_add3_u32 v242, v242, v243, v244
	v_add3_u32 v242, v242, v245, v246
	v_add3_u32 v242, v242, v247, v248
	v_add3_u32 v18, v18, v242, 7
	v_mul_lo_u32 v19, v18, s20
	v_add_u32_e32 v19, s30, v19
	v_lshl_add_u32 v21, v18, 7, s31
	v_add_u32_e32 v19, 0x20000, v19
	ds_read_u16 v21, v21
	ds_read_u16 v26, v19
	v_ashrrev_i32_e32 v19, 31, v18
	v_lshl_add_u64 v[22:23], s[96:97], 0, v[18:19]
	v_mov_b64_e32 v[24:25], s[82:83]
	v_mad_u64_u32 v[24:25], s[8:9], v22, s21, v[24:25]
	s_waitcnt lgkmcnt(1)
	v_sub_u32_e32 v20, v20, v21
	v_mad_i32_i24 v25, v23, s21, v25
	s_waitcnt lgkmcnt(0)
	v_lshlrev_b32_e32 v46, 1, v26
	v_ashrrev_i32_e32 v21, 31, v20
	v_lshl_add_u64 v[22:23], v[24:25], 0, v[46:47]
	v_lshl_add_u64 v[20:21], v[20:21], 1, v[22:23]
	global_load_ushort v19, v[20:21], off
